# P8 epilogue: cross-wave LDS exchange so each nt store writes 2 rows x 512 contiguous bytes (was 16 rows x 64B half-lines); wave owns 64 consecutive columns via B LDS read remap
# speedup vs baseline: 1.0159x; 1.0041x over previous
.LBB0_1716:
	s_add_u32 s51, s78, 0x4000000
	s_addc_u32 s52, s79, 0
	s_lshl_b32 s6, s6, 5
	s_and_b32 s12, s6, 0x60
	s_mov_b64 s[6:7], 0x80
	s_add_i32 m0, s29, 0x18000
	v_lshl_add_u64 v[6:7], v[6:7], 0, s[6:7]
	s_ashr_i32 s53, s33, 31
	s_lshl_b32 s9, s8, 13
	s_lshl_b32 s13, s12, 7
	s_waitcnt vmcnt(2)
	s_barrier
	global_load_lds_dwordx4 v[6:7], off
	v_lshl_add_u64 v[4:5], v[4:5], 0, s[6:7]
	s_add_i32 m0, s29, 0x1a000
	s_add_i32 s54, s29, 0x8000
	s_add_i32 s55, s29, 0xa000
	global_load_lds_dwordx4 v[4:5], off
	v_lshl_add_u64 v[0:1], v[0:1], 0, s[6:7]
	s_mov_b32 m0, s54
	s_add_u32 s10, s40, 0x40080
	global_load_lds_dwordx4 v[0:1], off
	v_lshl_add_u64 v[0:1], v[2:3], 0, s[6:7]
	s_mov_b32 m0, s55
	s_addc_u32 s11, s41, 0
	global_load_lds_dwordx4 v[0:1], off
	s_add_i32 m0, s29, 0x1c000
	v_lshl_add_u64 v[0:1], s[10:11], 0, v[132:133]
	global_load_lds_dwordx4 v[0:1], off
	v_lshl_add_u64 v[0:1], s[10:11], 0, v[128:129]
	s_add_i32 m0, s29, 0x1e000
	s_cmpk_lt_u32 s1, 0x100
	global_load_lds_dwordx4 v[0:1], off
	v_lshrrev_b32_e32 v1, 1, v9
	v_and_b32_e32 v1, 24, v1
	v_and_b32_e32 v0, 15, v9
	v_lshlrev_b32_e32 v2, 1, v1
	v_lshl_or_b32 v146, s8, 6, v0
	v_lshl_or_b32 v0, v0, 6, v2
	v_lshlrev_b32_e32 v2, 2, v9
	v_and_b32_e32 v2, 32, v2
	v_bitop3_b32 v3, v0, s9, v2 bitop3:0xde
	v_bitop3_b32 v147, v0, s13, v2 bitop3:0xde
	v_add_u32_e32 v147, s13, v147
	v_lshlrev_b32_e32 v0, 14, v13
	v_and_b32_e32 v0, 0xffff8000, v0
	v_or_b32_e32 v148, s12, v1
	v_lshrrev_b32_e64 v226, 5, s12
	v_lshl_add_u32 v226, s8, 2, v226
	v_bfe_u32 v227, v9, 5, 1
	v_lshl_add_u32 v227, v226, 2, v227
	v_lshrrev_b32_e32 v236, 4, v227
	v_and_b32_e32 v237, 15, v227
	v_lshl_or_b32 v146, v236, 6, v237
	v_and_b32_e32 v236, 31, v9
	v_lshlrev_b32_e32 v148, 3, v236
	v_mul_u32_u24_e32 v225, 0x210, v227
	v_lshl_add_u32 v225, v236, 4, v225
	v_add_u32_e32 v225, 0x20000, v225
	v_and_b32_e32 v236, 15, v9
	v_lshl_add_u32 v236, s8, 4, v236
	v_mul_u32_u24_e32 v224, 0x210, v236
	v_lshl_add_u32 v224, s12, 2, v224
	v_bfe_u32 v237, v9, 4, 2
	v_lshl_add_u32 v224, v237, 4, v224
	v_add_u32_e32 v224, 0x20000, v224
	s_mov_b64 s[98:99], 0x4000
	v_lshl_add_u32 v0, v12, 11, v0
	v_and_b32_e32 v1, 1, v13
	v_lshl_or_b32 v0, v1, 6, v0
	v_lshl_add_u32 v136, v14, 1, v0
	v_lshlrev_b32_e32 v0, 14, v8
	v_and_b32_e32 v0, 0xffff8000, v0
	s_waitcnt vmcnt(6)
	v_lshl_add_u32 v0, v10, 11, v0
	v_and_b32_e32 v1, 1, v8
	s_cselect_b64 s[8:9], -1, 0
	v_lshl_or_b32 v0, v1, 6, v0
	s_add_i32 s56, 0, 0x10000
	s_add_i32 s57, 0, 0x14000
	s_sext_i32_i16 s62, s0
	v_mov_b32_e32 v137, v133
	v_lshl_add_u32 v138, v11, 1, v0
	v_mov_b32_e32 v139, v133
	v_mov_b64_e32 v[140:141], 0x800
	v_mov_b64_e32 v[142:143], 0x7ff
	v_add_u32_e32 v149, s56, v147
	v_add_u32_e32 v150, 0x11000, v147
	v_add_u32_e32 v151, 0, v3
	s_mov_b64 s[10:11], 0x100000
	s_mov_b32 s58, 0x100000
	s_mov_b64 s[12:13], 0x120000
	s_mov_b32 s59, 0x120000
	s_mov_b64 s[14:15], 0x140000
	s_mov_b32 s60, 0x140000
	s_mov_b64 s[16:17], 0x160000
	s_mov_b32 s61, 0x160000
	s_barrier
	s_branch .LBB0_1719

.LBB0_1729:
	s_ashr_i32 s21, s62, 31
	s_lshr_b32 s21, s21, 28
	s_add_i32 s21, s62, s21
	s_ashr_i32 s30, s21, 4
	s_ashr_i32 s31, s30, 31
	s_lshl_b32 s19, s62, 8
	s_lshl_b64 s[40:41], s[30:31], 25
	s_add_u32 s40, s51, s40
	s_addc_u32 s41, s52, s41
	s_lshl_b32 s21, s30, 12
	s_sub_i32 s19, s19, s21
	v_lshl_add_u32 v152, s28, 8, v146
	v_or_b32_e32 v144, s19, v148
	v_ashrrev_i32_e32 v145, 31, v144
	v_ashrrev_i32_e32 v153, 31, v152
	v_lshl_add_u64 v[154:155], v[144:145], 1, s[40:41]
	v_lshlrev_b64 v[144:145], 13, v[152:153]
	v_lshl_add_u64 v[144:145], v[154:155], 0, v[144:145]
	v_cvt_pk_bf16_f32 v124, v124, v125
	v_cvt_pk_bf16_f32 v125, v126, v127
	v_cvt_pk_bf16_f32 v126, v120, v121
	v_cvt_pk_bf16_f32 v127, v122, v123
	ds_write_b128 v224, v[124:127]
	v_cvt_pk_bf16_f32 v112, v112, v113
	v_cvt_pk_bf16_f32 v113, v114, v115
	v_cvt_pk_bf16_f32 v114, v104, v105
	v_or_b32_e32 v104, 16, v152
	v_ashrrev_i32_e32 v105, 31, v104
	v_lshlrev_b64 v[104:105], 13, v[104:105]
	v_cvt_pk_bf16_f32 v115, v106, v107
	ds_write_b128 v224, v[112:115] offset:64
	v_lshl_add_u64 v[226:227], v[144:145], 0, s[98:99]
	s_waitcnt lgkmcnt(0)
	s_barrier
	ds_read_b128 v[228:231], v225
	ds_read_b128 v[232:235], v225 offset:1056
	s_waitcnt lgkmcnt(0)
	s_barrier
	global_store_dwordx4 v[144:145], v[228:231], off nt
	global_store_dwordx4 v[226:227], v[232:235], off nt
	s_nop 1
	v_lshl_add_u64 v[112:113], v[154:155], 0, v[104:105]
	v_cvt_pk_bf16_f32 v104, v116, v117
	v_cvt_pk_bf16_f32 v105, v118, v119
	v_cvt_pk_bf16_f32 v106, v108, v109
	v_cvt_pk_bf16_f32 v107, v110, v111
	ds_write_b128 v224, v[104:107]
	v_cvt_pk_bf16_f32 v96, v96, v97
	v_cvt_pk_bf16_f32 v97, v98, v99
	v_cvt_pk_bf16_f32 v98, v88, v89
	v_or_b32_e32 v88, 32, v152
	v_ashrrev_i32_e32 v89, 31, v88
	v_lshlrev_b64 v[88:89], 13, v[88:89]
	v_cvt_pk_bf16_f32 v99, v90, v91
	ds_write_b128 v224, v[96:99] offset:64
	v_lshl_add_u64 v[226:227], v[112:113], 0, s[98:99]
	s_waitcnt lgkmcnt(0)
	s_barrier
	ds_read_b128 v[228:231], v225
	ds_read_b128 v[232:235], v225 offset:1056
	s_waitcnt lgkmcnt(0)
	s_barrier
	global_store_dwordx4 v[112:113], v[228:231], off nt
	global_store_dwordx4 v[226:227], v[232:235], off nt
	s_nop 1
	v_lshl_add_u64 v[96:97], v[154:155], 0, v[88:89]
	v_cvt_pk_bf16_f32 v88, v100, v101
	v_cvt_pk_bf16_f32 v89, v102, v103
	v_cvt_pk_bf16_f32 v90, v92, v93
	v_cvt_pk_bf16_f32 v91, v94, v95
	ds_write_b128 v224, v[88:91]
	v_cvt_pk_bf16_f32 v80, v80, v81
	v_cvt_pk_bf16_f32 v81, v82, v83
	v_cvt_pk_bf16_f32 v82, v72, v73
	v_or_b32_e32 v72, 48, v152
	v_ashrrev_i32_e32 v73, 31, v72
	v_lshlrev_b64 v[72:73], 13, v[72:73]
	v_cvt_pk_bf16_f32 v83, v74, v75
	ds_write_b128 v224, v[80:83] offset:64
	v_lshl_add_u64 v[226:227], v[96:97], 0, s[98:99]
	s_waitcnt lgkmcnt(0)
	s_barrier
	ds_read_b128 v[228:231], v225
	ds_read_b128 v[232:235], v225 offset:1056
	s_waitcnt lgkmcnt(0)
	s_barrier
	global_store_dwordx4 v[96:97], v[228:231], off nt
	global_store_dwordx4 v[226:227], v[232:235], off nt
	s_nop 1
	v_lshl_add_u64 v[80:81], v[154:155], 0, v[72:73]
	v_cvt_pk_bf16_f32 v72, v84, v85
	v_cvt_pk_bf16_f32 v73, v86, v87
	v_cvt_pk_bf16_f32 v74, v76, v77
	v_cvt_pk_bf16_f32 v75, v78, v79
	ds_write_b128 v224, v[72:75]
	v_cvt_pk_bf16_f32 v68, v68, v69
	v_cvt_pk_bf16_f32 v69, v70, v71
	v_cvt_pk_bf16_f32 v70, v64, v65
	v_cvt_pk_bf16_f32 v71, v66, v67
	ds_write_b128 v224, v[68:71] offset:64
	v_lshl_add_u64 v[226:227], v[80:81], 0, s[98:99]
	s_waitcnt lgkmcnt(0)
	s_barrier
	ds_read_b128 v[228:231], v225
	ds_read_b128 v[232:235], v225 offset:1056
	s_waitcnt lgkmcnt(0)
	s_barrier
	global_store_dwordx4 v[80:81], v[228:231], off nt
	global_store_dwordx4 v[226:227], v[232:235], off nt
	v_cvt_pk_bf16_f32 v60, v60, v61
	v_cvt_pk_bf16_f32 v61, v62, v63
	v_cvt_pk_bf16_f32 v62, v56, v57
	v_add_co_u32_e32 v56, vcc, s58, v144
	v_lshl_add_u64 v[64:65], v[144:145], 0, s[10:11]
	s_nop 0
	v_addc_co_u32_e32 v57, vcc, 0, v145, vcc
	v_cvt_pk_bf16_f32 v63, v58, v59
	ds_write_b128 v224, v[60:63]
	v_cvt_pk_bf16_f32 v48, v48, v49
	v_cvt_pk_bf16_f32 v49, v50, v51
	v_cvt_pk_bf16_f32 v50, v40, v41
	v_cvt_pk_bf16_f32 v51, v42, v43
	ds_write_b128 v224, v[48:51] offset:64
	v_lshl_add_u64 v[226:227], v[64:65], 0, s[98:99]
	s_waitcnt lgkmcnt(0)
	s_barrier
	ds_read_b128 v[228:231], v225
	ds_read_b128 v[232:235], v225 offset:1056
	s_waitcnt lgkmcnt(0)
	s_barrier
	global_store_dwordx4 v[56:57], v[228:231], off nt
	global_store_dwordx4 v[226:227], v[232:235], off nt
	v_cvt_pk_bf16_f32 v40, v52, v53
	v_cvt_pk_bf16_f32 v41, v54, v55
	v_cvt_pk_bf16_f32 v42, v44, v45
	v_add_co_u32_e32 v44, vcc, s59, v144
	s_nop 0
	v_lshl_add_u64 v[48:49], v[144:145], 0, s[12:13]
	v_addc_co_u32_e32 v45, vcc, 0, v145, vcc
	v_cvt_pk_bf16_f32 v43, v46, v47
	ds_write_b128 v224, v[40:43]
	v_cvt_pk_bf16_f32 v32, v32, v33
	v_cvt_pk_bf16_f32 v33, v34, v35
	v_cvt_pk_bf16_f32 v34, v24, v25
	v_cvt_pk_bf16_f32 v35, v26, v27
	ds_write_b128 v224, v[32:35] offset:64
	v_lshl_add_u64 v[226:227], v[48:49], 0, s[98:99]
	s_waitcnt lgkmcnt(0)
	s_barrier
	ds_read_b128 v[228:231], v225
	ds_read_b128 v[232:235], v225 offset:1056
	s_waitcnt lgkmcnt(0)
	s_barrier
	global_store_dwordx4 v[44:45], v[228:231], off nt
	global_store_dwordx4 v[226:227], v[232:235], off nt
	v_cvt_pk_bf16_f32 v24, v36, v37
	v_cvt_pk_bf16_f32 v25, v38, v39
	v_cvt_pk_bf16_f32 v26, v28, v29
	v_add_co_u32_e32 v28, vcc, s60, v144
	s_nop 0
	v_lshl_add_u64 v[32:33], v[144:145], 0, s[14:15]
	v_addc_co_u32_e32 v29, vcc, 0, v145, vcc
	v_cvt_pk_bf16_f32 v27, v30, v31
	ds_write_b128 v224, v[24:27]
	v_cvt_pk_bf16_f32 v16, v16, v17
	v_cvt_pk_bf16_f32 v17, v18, v19
	v_cvt_pk_bf16_f32 v18, v8, v9
	v_cvt_pk_bf16_f32 v19, v10, v11
	ds_write_b128 v224, v[16:19] offset:64
	v_lshl_add_u64 v[226:227], v[32:33], 0, s[98:99]
	s_waitcnt lgkmcnt(0)
	s_barrier
	ds_read_b128 v[228:231], v225
	ds_read_b128 v[232:235], v225 offset:1056
	s_waitcnt lgkmcnt(0)
	s_barrier
	global_store_dwordx4 v[28:29], v[228:231], off nt
	global_store_dwordx4 v[226:227], v[232:235], off nt
	v_cvt_pk_bf16_f32 v8, v20, v21
	v_cvt_pk_bf16_f32 v9, v22, v23
	v_cvt_pk_bf16_f32 v10, v12, v13
	v_add_co_u32_e32 v12, vcc, s61, v144
	s_nop 0
	v_lshl_add_u64 v[16:17], v[144:145], 0, s[16:17]
	v_addc_co_u32_e32 v13, vcc, 0, v145, vcc
	s_andn2_b64 vcc, exec, s[0:1]
	s_mov_b64 s[0:1], -1
	v_cvt_pk_bf16_f32 v11, v14, v15
	ds_write_b128 v224, v[8:11]
	v_cvt_pk_bf16_f32 v4, v4, v5
	v_cvt_pk_bf16_f32 v5, v6, v7
	v_cvt_pk_bf16_f32 v6, v0, v1
	v_cvt_pk_bf16_f32 v7, v2, v3
	ds_write_b128 v224, v[4:7] offset:64
	v_lshl_add_u64 v[226:227], v[16:17], 0, s[98:99]
	s_waitcnt lgkmcnt(0)
	s_barrier
	ds_read_b128 v[228:231], v225
	ds_read_b128 v[232:235], v225 offset:1056
	s_waitcnt lgkmcnt(0)
	s_barrier
	global_store_dwordx4 v[12:13], v[228:231], off nt
	global_store_dwordx4 v[226:227], v[232:235], off nt
	s_cbranch_vccnz .LBB0_1718
	s_andn2_b64 vcc, exec, s[4:5]
	s_cbranch_vccnz .LBB0_1717
	s_barrier
	s_branch .LBB0_1717
